# lever 4 re-test on the current stack: one static s_setprio 1 for waves 4-7 at attention entry (reset at exit), no per-segment toggling
# speedup vs baseline: 1.0135x; 1.0062x over previous
; __device__ __forceinline__ int lane_op() { unsigned z = 0u; asm volatile("" : "+v"(z)); return (int)__builtin_amdgcn_mbcnt_hi(~0u, __builtin_amdgcn_mbcnt_lo(~0u, z)); }
; #define PH_ON(bit) if constexpr ((PHMASK & (bit)) != 0)
; __global__ void __launch_bounds__(NTHREADS, 2) fwd_megakernel(Args a_unused) {
;     ...
;                 const int per = (1024 + G - 1) / G;
;                 PH_ON(512) {
;                     const int lane = lane_op();
;                     const float la = wave_sum(ap->in[I_LQ1][l * 64 + lane] * ap->in[I_LK1][l * 64 + lane]), lb = wave_sum(ap->in[I_LQ2][l * 64 + lane] * ap->in[I_LK2][l * 64 + lane]);
;                     const float lam_init = 0.8f - 0.6f * expf(-0.3f * (float)l);
;                     const float lam = __int_as_float(__builtin_amdgcn_readfirstlane(__float_as_int(expf(la) - expf(lb) + lam_init)));
;                     const float oscale = __int_as_float(__builtin_amdgcn_readfirstlane(__float_as_int(1.0f - lam_init)));
;                     const float* subg = ap->in[I_SUBG] + l * 128;
;                     if constexpr (PROBE_ATT2 != 0) { for (int i = 0; i < per; ++i) { const int u = vcu * per + i; if (u < 1024) attn_unit<false>(lds, (bf16_t*)(ws + WS_Q), (const bf16_t*)(ws + WS_K), (const bf16_t*)(ws + WS_VT), subg, lam, oscale, u, wave); } }
;                     for (int i = 0; i < per; ++i) { int u = vcu * per + i;
.LBB0_571:
	s_and_b64 vcc, exec, s[12:13]
	s_cbranch_vccz .LBB0_854
	v_mov_b32_e32 v0, v1
	s_load_dwordx8 s[40:47], s[0:1], 0x48
	v_mbcnt_lo_u32_b32 v0, -1, v0
	v_readlane_b32 s12, v254, 60
	v_mbcnt_hi_u32_b32 v0, -1, v0
	s_waitcnt lgkmcnt(0)
	s_mov_b32 s14, s12
	v_lshl_add_u32 v2, s14, 6, v0
	v_ashrrev_i32_e32 v3, 31, v2
	v_lshlrev_b64 v[2:3], 2, v[2:3]
	v_lshl_add_u64 v[4:5], s[40:41], 0, v[2:3]
	global_load_dword v0, v[4:5], off
	v_lshl_add_u64 v[4:5], s[42:43], 0, v[2:3]
	global_load_dword v6, v[4:5], off
	v_mov_b32_e32 v7, v195
	v_lshl_add_u64 v[4:5], s[44:45], 0, v[2:3]
	v_lshl_add_u64 v[2:3], s[46:47], 0, v[2:3]
	global_load_dword v4, v[4:5], off
	s_abs_i32 s7, s29
	global_load_dword v2, v[2:3], off
	v_cvt_f32_i32_e32 v5, s14
	v_cvt_f32_u32_e32 v8, s7
	s_mov_b32 s19, 0x3fb8aa3b
	s_add_i32 s12, s29, 0x3ff
	v_mul_f32_e32 v5, 0xbe99999a, v5
	v_rcp_iflag_f32_e32 v8, v8
	v_mul_f32_e32 v9, 0x3fb8aa3b, v5
	v_fma_f32 v10, v5, s19, -v9
	v_rndne_f32_e32 v11, v9
	v_fmac_f32_e32 v10, 0x32a5705f, v5
	v_sub_f32_e32 v9, v9, v11
	v_add_f32_e32 v9, v9, v10
	v_cvt_i32_f32_e32 v11, v11
	v_mul_f32_e32 v8, 0x4f7ffffe, v8
	v_exp_f32_e32 v9, v9
	v_cvt_u32_f32_e32 v8, v8
	s_mov_b32 s20, 0xc2ce8ed0
	v_readlane_b32 s13, v254, 61
	v_mov_b32_e32 v3, v195
	s_xor_b32 s14, s12, s29
	v_ldexp_f32 v9, v9, v11
	v_cmp_ngt_f32_e32 vcc, s20, v5
	s_mov_b32 s21, 0x42b17218
	s_abs_i32 s13, s12
	s_ashr_i32 s12, s14, 31
	v_lshlrev_b32_e32 v7, 2, v7
	v_readfirstlane_b32 s14, v8
	v_cndmask_b32_e32 v8, 0, v9, vcc
	v_cmp_nlt_f32_e32 vcc, s21, v5
	v_mov_b32_e32 v11, 0x7f800000
	v_lshlrev_b32_e32 v3, 2, v3
	v_xor_b32_e32 v10, 4, v7
	v_cndmask_b32_e32 v5, v11, v8, vcc
	v_xor_b32_e32 v16, 4, v3
	v_xor_b32_e32 v12, 8, v7
	v_xor_b32_e32 v17, 8, v3
	v_xor_b32_e32 v13, 16, v7
	v_xor_b32_e32 v18, 16, v3
	v_xor_b32_e32 v14, 32, v7
	v_xor_b32_e32 v19, 32, v3
	v_xor_b32_e32 v15, 64, v7
	v_xor_b32_e32 v20, 64, v3
	v_xor_b32_e32 v7, 0x80, v7
	v_xor_b32_e32 v3, 0x80, v3
	s_sub_i32 s15, 0, s7
	s_mul_i32 s15, s15, s14
	s_mul_hi_u32 s15, s14, s15
	s_add_i32 s14, s14, s15
	s_mul_hi_u32 s14, s13, s14
	s_mul_i32 s16, s14, s7
	s_sub_i32 s13, s13, s16
	s_add_i32 s18, s14, 1
	s_sub_i32 s16, s13, s7
	s_cmp_ge_u32 s13, s7
	s_cselect_b32 s14, s18, s14
	s_cselect_b32 s13, s16, s13
	s_add_i32 s16, s14, 1
	s_cmp_ge_u32 s13, s7
	s_cselect_b32 s7, s16, s14
	s_xor_b32 s7, s7, s12
	s_sub_i32 s7, s7, s12
	s_cmp_gt_i32 s7, 0
	s_cselect_b64 s[12:13], -1, 0
	v_writelane_b32 v254, s12, 62
	s_cmp_lt_i32 s7, 1
	s_waitcnt vmcnt(0)
	v_mul_f32_e32 v8, v0, v6
	ds_bpermute_b32 v8, v10, v8
	v_mov_b32_e32 v10, 0x3f4ccccd
	v_fmamk_f32 v5, v5, 0xbf19999a, v10
	v_writelane_b32 v254, s13, 63
	v_readfirstlane_b32 s15, v5
	s_waitcnt lgkmcnt(0)
	v_fmac_f32_e32 v8, v0, v6
	v_mul_f32_e32 v9, v4, v2
	ds_bpermute_b32 v9, v16, v9
	ds_bpermute_b32 v0, v12, v8
	v_readlane_b32 s12, v254, 59
	s_mul_i32 s39, s7, s12
	s_waitcnt lgkmcnt(1)
	v_fmac_f32_e32 v9, v4, v2
	ds_bpermute_b32 v2, v17, v9
	s_waitcnt lgkmcnt(1)
	v_add_f32_e32 v0, v8, v0
	ds_bpermute_b32 v4, v13, v0
	s_waitcnt lgkmcnt(1)
	v_add_f32_e32 v2, v9, v2
	ds_bpermute_b32 v6, v18, v2
	s_waitcnt lgkmcnt(1)
	v_add_f32_e32 v0, v0, v4
	ds_bpermute_b32 v4, v14, v0
	s_waitcnt lgkmcnt(1)
	v_add_f32_e32 v2, v2, v6
	ds_bpermute_b32 v6, v19, v2
	s_waitcnt lgkmcnt(1)
	v_add_f32_e32 v0, v0, v4
	ds_bpermute_b32 v4, v15, v0
	s_waitcnt lgkmcnt(1)
	v_add_f32_e32 v2, v2, v6
	ds_bpermute_b32 v6, v20, v2
	s_waitcnt lgkmcnt(1)
	v_add_f32_e32 v0, v0, v4
	ds_bpermute_b32 v4, v7, v0
	s_waitcnt lgkmcnt(1)
	v_add_f32_e32 v2, v2, v6
	ds_bpermute_b32 v3, v3, v2
	s_waitcnt lgkmcnt(1)
	v_add_f32_e32 v0, v0, v4
	v_cmp_ngt_f32_e32 vcc, s20, v0
	s_waitcnt lgkmcnt(0)
	v_add_f32_e32 v2, v2, v3
	v_mul_f32_e32 v3, 0x3fb8aa3b, v0
	v_mul_f32_e32 v4, 0x3fb8aa3b, v2
	v_fma_f32 v6, v0, s19, -v3
	v_rndne_f32_e32 v7, v3
	v_fma_f32 v8, v2, s19, -v4
	v_rndne_f32_e32 v9, v4
	v_fmac_f32_e32 v6, 0x32a5705f, v0
	v_sub_f32_e32 v3, v3, v7
	v_fmac_f32_e32 v8, 0x32a5705f, v2
	v_sub_f32_e32 v4, v4, v9
	v_add_f32_e32 v3, v3, v6
	v_cvt_i32_f32_e32 v7, v7
	v_add_f32_e32 v4, v4, v8
	v_exp_f32_e32 v3, v3
	v_cvt_i32_f32_e32 v9, v9
	v_exp_f32_e32 v4, v4
	v_ldexp_f32 v3, v3, v7
	v_cndmask_b32_e32 v3, 0, v3, vcc
	v_ldexp_f32 v4, v4, v9
	v_cmp_ngt_f32_e32 vcc, s20, v2
	s_nop 1
	v_cndmask_b32_e32 v4, 0, v4, vcc
	v_cmp_nlt_f32_e32 vcc, s21, v0
	s_nop 1
	v_cndmask_b32_e32 v0, v11, v3, vcc
	v_cmp_nlt_f32_e32 vcc, s21, v2
	s_nop 1
	v_cndmask_b32_e32 v2, v11, v4, vcc
	v_sub_f32_e32 v0, v0, v2
	v_add_f32_e32 v0, v5, v0
	s_nop 0
	v_readfirstlane_b32 s14, v0
	s_cbranch_scc1 .LBB0_672
	v_readlane_b32 s100, v254, 48
	s_cmp_lt_u32 s100, 4
	s_cbranch_scc1 .Lattn_noprio
	s_setprio 1
.Lattn_noprio:
	s_load_dwordx2 s[12:13], s[0:1], 0x68
	v_readlane_b32 s18, v254, 60
	v_readlane_b32 s19, v254, 61
	s_lshl_b32 s18, s18, 7
	s_ashr_i32 s19, s18, 31
	s_lshl_b64 s[18:19], s[18:19], 2
	s_waitcnt lgkmcnt(0)
	s_add_u32 s44, s12, s18
	s_addc_u32 s45, s13, s19
	s_cmpk_eq_i32 s29, 0x100
	v_readlane_b32 s13, v254, 59
	s_cselect_b64 s[46:47], -1, 0
	s_lshl_b32 s12, s13, 2
	s_and_b32 s12, s12, 0xffffff80
	s_and_b32 s13, s13, 31
	s_or_b32 s60, s12, s13
	s_add_u32 s48, s10, 0xed00000
	s_addc_u32 s49, s11, 0
	s_add_u32 s50, s10, 0x8d00000
	s_addc_u32 s51, s11, 0
	s_add_u32 s52, s10, 0xad00000
	v_sub_f32_e64 v192, 1.0, s15
	s_addc_u32 s53, s11, 0
	s_mov_b32 s15, s14
	s_mov_b32 s61, 0
	s_branch .LBB0_576

; #define PH_ON(bit) if constexpr ((PHMASK & (bit)) != 0)
; __global__ void __launch_bounds__(NTHREADS, 2) fwd_megakernel(Args a_unused) {
;     ...
;                 PH_ON(1024) {
;                     const float* cw = ap->in[I_CONVW] + (size_t)l * 31 * DM; const float* cb = ap->in[I_CONVB] + l * DM; const float* lg = ap->in[I_CLNG] + l * DM; const float* lb2 = ap->in[I_CLNB] + l * DM;
;                     for (int rep_ = 0; rep_ < 1 + PROBE_CONV2; ++rep_) { const int u0 = vcu * per; int nun = 1024 - u0; nun = nun < 0 ? 0 : (nun > per ? per : nun);
;                         if ((128 % per) == 0) conv_run(lds, (const bf16_t*)(ws + WS_AG), (bf16_t*)(ws + WS_CA), cw, cb, lg, lb2, u0, nun, wave);
;                         else for (int i = 0; i < nun; ++i) conv_run(lds, (const bf16_t*)(ws + WS_AG), (bf16_t*)(ws + WS_CA), cw, cb, lg, lb2, u0 + i, 1, wave); }
.LBB0_672:
	s_setprio 0
	s_load_dwordx8 s[40:47], s[0:1], 0x28
	v_readlane_b32 s12, v254, 60
	v_readlane_b32 s13, v254, 61
	s_mov_b32 s14, s12
	s_mul_i32 s13, s14, 0x1f000
	s_mul_hi_i32 s12, s12, 0x1f000
	s_waitcnt lgkmcnt(0)
	s_add_u32 s52, s40, s13
	s_addc_u32 s53, s41, s12
	s_lshl_b32 s12, s14, 10
	s_ashr_i32 s13, s12, 31
	s_lshl_b64 s[12:13], s[12:13], 2
	s_add_u32 s14, s42, s12
	s_addc_u32 s15, s43, s13
	s_add_u32 s34, s44, s12
	s_addc_u32 s35, s45, s13
	s_add_u32 s46, s46, s12
	v_writelane_b32 v255, s12, 0
	s_addc_u32 s47, s47, s13
	s_nop 0
	v_writelane_b32 v255, s13, 1
	s_sub_i32 s12, 0x400, s39
	s_min_i32 s12, s12, s7
	s_cmpk_lt_i32 s39, 0x401
	s_cselect_b32 s16, s12, 0
	s_abs_i32 s12, s7
	v_cvt_f32_u32_e32 v0, s12
	s_sub_i32 s13, 0, s12
	v_rcp_iflag_f32_e32 v0, v0
	s_nop 0
	v_mul_f32_e32 v0, 0x4f7ffffe, v0
	v_cvt_u32_f32_e32 v0, v0
	s_nop 0
	v_readfirstlane_b32 s18, v0
	s_mul_i32 s13, s13, s18
	s_mul_hi_u32 s13, s18, s13
	s_add_i32 s18, s18, s13
	s_lshr_b32 s13, s18, 25
	s_mul_i32 s13, s13, s12
	s_sub_i32 s13, 0x80, s13
	s_sub_i32 s18, s13, s12
	s_cmp_ge_u32 s13, s12
	s_cselect_b32 s13, s18, s13
	s_sub_i32 s18, s13, s12
	s_cmp_ge_u32 s13, s12
	s_cselect_b32 s18, s18, s13
	s_add_u32 s48, s10, 0x6d00000
	s_addc_u32 s49, s11, 0
	s_add_u32 s50, s10, 0x4d00000
	s_addc_u32 s51, s11, 0
	s_cmp_gt_i32 s16, 0
	s_cselect_b64 s[12:13], -1, 0
	v_cndmask_b32_e64 v0, 0, 1, s[12:13]
	v_cmp_ne_u32_e64 s[12:13], 1, v0
	s_cmp_lg_u32 s18, 0
	s_nop 0
	v_writelane_b32 v255, s12, 2
	s_nop 1
	v_writelane_b32 v255, s13, 3
	s_cbranch_scc0 .LBB0_741
	s_and_b64 vcc, exec, s[12:13]
	s_cbranch_vccnz .LBB0_740
	v_readlane_b32 s12, v254, 59
	s_mul_i32 s12, s7, s12
	s_lshl_b32 s12, s12, 4
	s_or_b32 s54, s12, 15
	s_mov_b32 s18, s16
	s_branch .LBB0_676

; __global__ void __launch_bounds__(NTHREADS, 2) fwd_megakernel(Args a_unused) {
	.amdhsa_kernel _Z14fwd_megakernel4Args
		.amdhsa_group_segment_fixed_size 0
		.amdhsa_private_segment_fixed_size 0
		.amdhsa_kernarg_size 488
		.amdhsa_user_sgpr_count 2
		.amdhsa_user_sgpr_dispatch_ptr 0
		.amdhsa_user_sgpr_queue_ptr 0
		.amdhsa_user_sgpr_kernarg_segment_ptr 1
		.amdhsa_user_sgpr_dispatch_id 0
		.amdhsa_user_sgpr_kernarg_preload_length 0
		.amdhsa_user_sgpr_kernarg_preload_offset 0
		.amdhsa_user_sgpr_private_segment_size 0
		.amdhsa_uses_dynamic_stack 0
		.amdhsa_enable_private_segment 0
		.amdhsa_system_sgpr_workgroup_id_x 1
		.amdhsa_system_sgpr_workgroup_id_y 0
		.amdhsa_system_sgpr_workgroup_id_z 0
		.amdhsa_system_sgpr_workgroup_info 0
		.amdhsa_system_vgpr_workitem_id 2
		.amdhsa_next_free_vgpr 256
		.amdhsa_next_free_sgpr 102
		.amdhsa_accum_offset 256
		.amdhsa_reserve_vcc 1
		.amdhsa_float_round_mode_32 0
		.amdhsa_float_round_mode_16_64 0
		.amdhsa_float_denorm_mode_32 3
		.amdhsa_float_denorm_mode_16_64 3
		.amdhsa_dx10_clamp 1
		.amdhsa_ieee_mode 1
		.amdhsa_fp16_overflow 0
		.amdhsa_tg_split 0
		.amdhsa_exception_fp_ieee_invalid_op 0
		.amdhsa_exception_fp_denorm_src 0
		.amdhsa_exception_fp_ieee_div_zero 0
		.amdhsa_exception_fp_ieee_overflow 0
		.amdhsa_exception_fp_ieee_underflow 0
		.amdhsa_exception_fp_ieee_inexact 0
		.amdhsa_exception_int_div_zero 0
	.end_amdhsa_kernel

; __global__ void __launch_bounds__(NTHREADS, 2) fwd_megakernel(Args a_unused) {
amdhsa.kernels:
  - .agpr_count:     0
    .args:
      - .offset:         0
        .size:           232
        .value_kind:     by_value
      - .offset:         232
        .size:           4
        .value_kind:     hidden_block_count_x
      - .offset:         236
        .size:           4
        .value_kind:     hidden_block_count_y
      - .offset:         240
        .size:           4
        .value_kind:     hidden_block_count_z
      - .offset:         244
        .size:           2
        .value_kind:     hidden_group_size_x
      - .offset:         246
        .size:           2
        .value_kind:     hidden_group_size_y
      - .offset:         248
        .size:           2
        .value_kind:     hidden_group_size_z
      - .offset:         250
        .size:           2
        .value_kind:     hidden_remainder_x
      - .offset:         252
        .size:           2
        .value_kind:     hidden_remainder_y
      - .offset:         254
        .size:           2
        .value_kind:     hidden_remainder_z
      - .offset:         272
        .size:           8
        .value_kind:     hidden_global_offset_x
      - .offset:         280
        .size:           8
        .value_kind:     hidden_global_offset_y
      - .offset:         288
        .size:           8
        .value_kind:     hidden_global_offset_z
      - .offset:         296
        .size:           2
        .value_kind:     hidden_grid_dims
      - .offset:         320
        .size:           8
        .value_kind:     hidden_multigrid_sync_arg
      - .offset:         352
        .size:           4
        .value_kind:     hidden_dynamic_lds_size
    .group_segment_fixed_size: 0
    .kernarg_segment_align: 8
    .kernarg_segment_size: 488
    .language:       OpenCL C
    .language_version:
      - 2
      - 0
    .max_flat_workgroup_size: 512
    .name:           _Z14fwd_megakernel4Args
    .private_segment_fixed_size: 0
    .sgpr_count:     108
    .sgpr_spill_count: 137
    .symbol:         _Z14fwd_megakernel4Args.kd
    .uniform_work_group_size: 1
    .uses_dynamic_stack: false
    .vgpr_count:     256
    .vgpr_spill_count: 0
    .wavefront_size: 64
